# GEMM phase prologues: second K-tile load batch issued before the first vmcnt wait (one exposed latency instead of two)
# baseline (speedup 1.0000x reference)
; #define PG8_STAGE(bufoff, gbase, voff) do { _Pragma("unroll") for (int _i = 0; _i < 2; ++_i) \
;         __builtin_amdgcn_global_load_lds((const unsigned*)((const char*)(gbase) + (voff)[_i]), (LAS unsigned*)(lds + (bufoff) + ldsw + _i * 8192), 16, 0, 0); } while (0)
; #define PG8_WAIT_V(n) asm volatile("s_waitcnt vmcnt(" #n ")" ::: "memory")
; #define PG8_BAR __builtin_amdgcn_s_barrier()
; template <class Epi, class Sched>
; __device__ __forceinline__ void gemm_phase(LAS unsigned char* lds, const Gemm g, const Sched& S, const Epi& E) {
;     ...
;     unsigned voffA[2], voffB[2];
; #pragma unroll
;     for (int i = 0; i < 2; ++i) { int R, C; stage_rc(tid * 16 + i * 8192, R, C); const int Rb = Epi::PERM ? ((R & ~31) + perm32(R & 31)) : R;
;         voffA[i] = (unsigned)(R * g.lda + C) * 2u; voffB[i] = (unsigned)(Rb * K + C) * 2u; }
;     const size_t kstep = (size_t)(BK * 2);
;     const size_t hstepA = (size_t)HALF * g.lda * 2, hstepB = (size_t)HALF * K * 2;
;     const size_t tstepA = 2 * hstepA, tstepB = 2 * hstepB;
;     const unsigned ldsw = (unsigned)wid * 1024u;
;     const int aoff = lds_byte(wr * 64 + fr, fq * 8), boff = lds_byte(wc * 32 + fr, fq * 8);
;     ...
;     Unit cur, nxt; int ui = 0;
;     if (!S.next(0, cur)) return;
;     f32x4 acc[2][2][4][2];
; #pragma unroll
;     for (int a = 0; a < 2; ++a)
; #pragma unroll
;         for (int b = 0; b < 2; ++b)
; #pragma unroll
;             for (int m = 0; m < 4; ++m)
; #pragma unroll
;                 for (int n = 0; n < 2; ++n) acc[a][b][m][n] = (f32x4){0.f, 0.f, 0.f, 0.f};
;     bf16x8 At[4][2], B0[2][2], B1[2][2];
;     const char* cA = (const char*)g.A + (size_t)cur.b * g.abs * 2 + (size_t)cur.pm * tstepA;
;     const char* cB = (const char*)g.Bt + (size_t)cur.b * g.bbs * 2 + (size_t)cur.pn * tstepB;
;     PG8_STAGE(PG8_SB(0, 0), cB, voffB); PG8_STAGE(PG8_SB(0, 1), cB + hstepB, voffB); PG8_STAGE(PG8_SA(0, 0), cA, voffA); PG8_STAGE(PG8_SA(0, 1), cA + hstepA, voffA);
;     if (wr == 1) PG8_BAR;
;     PG8_WAIT_V(2); PG8_BAR;
;     PG8_STAGE(PG8_SB(1, 0), cB + kstep, voffB); PG8_STAGE(PG8_SA(1, 0), cA + kstep, voffA); PG8_STAGE(PG8_SB(1, 1), cB + hstepB + kstep, voffB);
;     PG8_WAIT_V(6); PG8_BAR;
.LBB0_19:
	v_readlane_b32 s16, v254, 56
	v_mov_b32_e32 v201, v213
	v_readlane_b32 s17, v254, 57
	v_mov_b32_e32 v197, v213
	v_readlane_b32 s40, v254, 52
	v_lshl_add_u64 v[8:9], s[16:17], 0, v[200:201]
	v_lshl_add_u64 v[10:11], s[16:17], 0, v[196:197]
	v_mov_b32_e32 v203, v213
	v_readlane_b32 s41, v254, 53
	s_add_i32 m0, s6, 0x18000
	v_lshl_add_u64 v[8:9], v[8:9], 0, s[12:13]
	v_lshl_add_u64 v[12:13], s[40:41], 0, v[202:203]
	v_mov_b32_e32 v199, v213
	global_load_lds_dwordx4 v[8:9], off
	v_lshl_add_u64 v[8:9], v[10:11], 0, s[12:13]
	s_add_i32 m0, s6, 0x1a000
	s_add_i32 s47, s6, 0x8000
	v_lshl_add_u64 v[14:15], s[40:41], 0, v[198:199]
	global_load_lds_dwordx4 v[8:9], off
	v_lshl_add_u64 v[8:9], v[12:13], 0, s[12:13]
	s_mov_b32 m0, s47
	s_add_i32 s48, s6, 0xa000
	v_readlane_b32 s18, v254, 58
	global_load_lds_dwordx4 v[8:9], off
	v_lshl_add_u64 v[8:9], v[14:15], 0, s[12:13]
	s_mov_b32 m0, s48
	v_readlane_b32 s19, v254, 59
	global_load_lds_dwordx4 v[8:9], off
	s_add_i32 m0, s6, 0x1c000
	v_lshl_add_u64 v[8:9], s[18:19], 0, v[200:201]
	global_load_lds_dwordx4 v[8:9], off
	v_lshl_add_u64 v[8:9], s[18:19], 0, v[196:197]
	s_add_i32 m0, s6, 0x1e000
	v_lshrrev_b32_e32 v7, 1, v1
	global_load_lds_dwordx4 v[8:9], off
	s_waitcnt vmcnt(8)
	s_barrier
	v_and_b32_e32 v7, 24, v7
	v_and_b32_e32 v220, 15, v1
	v_lshlrev_b32_e32 v8, 1, v7
	v_lshlrev_b32_e32 v1, 2, v1
	s_lshl_b32 s1, s1, 5
	s_lshl_b32 s49, s14, 6
	v_lshl_or_b32 v8, v220, 6, v8
	s_lshl_b32 s14, s14, 13
	v_and_b32_e32 v1, 32, v1
	s_and_b32 s1, s1, 0x60
	v_bitop3_b32 v9, v8, s14, v1 bitop3:0xde
	s_lshl_b32 s14, s1, 7
	v_bitop3_b32 v221, v8, s14, v1 bitop3:0xde
	v_lshlrev_b32_e32 v1, 10, v220
	v_or3_b32 v8, v7, v1, s1
	v_lshlrev_b32_e32 v1, 14, v5
	v_and_b32_e32 v1, 0xffff8000, v1
	v_lshl_add_u32 v1, v4, 11, v1
	v_and_b32_e32 v4, 1, v5
	v_lshl_or_b32 v1, v4, 6, v1
	v_lshl_add_u32 v204, v6, 1, v1
	v_lshlrev_b32_e32 v1, 14, v0
	v_and_b32_e32 v1, 0xffff8000, v1
	v_lshl_add_u32 v1, v2, 11, v1
	v_and_b32_e32 v0, 1, v0
	v_lshl_or_b32 v0, v0, 6, v1
	s_waitcnt vmcnt(6)
	v_lshl_add_u32 v206, v3, 1, v0
	v_mov_b32_e32 v2, v213
	v_mov_b32_e32 v3, v213
	s_cmpk_lt_u32 s0, 0x100
	v_or_b32_e32 v222, s1, v7
	v_mov_b32_e32 v0, v213
	v_mov_b32_e32 v1, v213
	v_add_u32_e32 v223, 0, v9
	v_lshlrev_b32_e32 v212, 1, v8
	v_mov_b64_e32 v[6:7], v[2:3]
	v_mov_b64_e32 v[18:19], v[2:3]
	v_mov_b64_e32 v[22:23], v[2:3]
	v_mov_b64_e32 v[34:35], v[2:3]
	v_mov_b64_e32 v[38:39], v[2:3]
	v_mov_b64_e32 v[66:67], v[2:3]
	s_waitcnt lgkmcnt(0)
	v_mov_b64_e32 v[70:71], v[2:3]
	v_mov_b64_e32 v[10:11], v[2:3]
	v_mov_b64_e32 v[14:15], v[2:3]
	v_mov_b64_e32 v[26:27], v[2:3]
	v_mov_b64_e32 v[30:31], v[2:3]
	v_mov_b64_e32 v[50:51], v[2:3]
	v_mov_b64_e32 v[54:55], v[2:3]
	v_mov_b64_e32 v[82:83], v[2:3]
	v_mov_b64_e32 v[86:87], v[2:3]
	v_mov_b64_e32 v[102:103], v[2:3]
	v_mov_b64_e32 v[106:107], v[2:3]
	v_mov_b64_e32 v[142:143], v[2:3]
	v_mov_b64_e32 v[146:147], v[2:3]
	v_mov_b64_e32 v[166:167], v[2:3]
	v_mov_b64_e32 v[170:171], v[2:3]
	v_mov_b64_e32 v[182:183], v[2:3]
	v_mov_b64_e32 v[186:187], v[2:3]
	v_mov_b64_e32 v[122:123], v[2:3]
	v_mov_b64_e32 v[126:127], v[2:3]
	v_mov_b64_e32 v[134:135], v[2:3]
	v_mov_b64_e32 v[138:139], v[2:3]
	v_mov_b64_e32 v[94:95], v[2:3]
	v_mov_b64_e32 v[98:99], v[2:3]
	v_mov_b64_e32 v[58:59], v[2:3]
	v_mov_b64_e32 v[62:63], v[2:3]
	v_readlane_b32 s0, v254, 36
	s_cselect_b64 s[18:19], -1, 0
	v_mov_b32_e32 v205, v213
	v_mov_b32_e32 v207, v213
	s_mov_b32 s42, 0
	v_mov_b64_e32 v[4:5], v[0:1]
	v_mov_b64_e32 v[16:17], v[0:1]
	v_mov_b64_e32 v[20:21], v[0:1]
	v_mov_b64_e32 v[32:33], v[0:1]
	v_mov_b64_e32 v[36:37], v[0:1]
	v_mov_b64_e32 v[64:65], v[0:1]
	v_mov_b64_e32 v[68:69], v[0:1]
	v_mov_b64_e32 v[8:9], v[0:1]
	v_mov_b64_e32 v[12:13], v[0:1]
	v_mov_b64_e32 v[24:25], v[0:1]
	v_mov_b64_e32 v[28:29], v[0:1]
	v_mov_b64_e32 v[48:49], v[0:1]
	v_mov_b64_e32 v[52:53], v[0:1]
	v_mov_b64_e32 v[80:81], v[0:1]
	v_mov_b64_e32 v[84:85], v[0:1]
	v_mov_b64_e32 v[100:101], v[0:1]
	v_mov_b64_e32 v[104:105], v[0:1]
	v_mov_b64_e32 v[140:141], v[0:1]
	v_mov_b64_e32 v[144:145], v[0:1]
	v_mov_b64_e32 v[164:165], v[0:1]
	v_mov_b64_e32 v[168:169], v[0:1]
	v_mov_b64_e32 v[180:181], v[0:1]
	v_mov_b64_e32 v[184:185], v[0:1]
	v_mov_b64_e32 v[120:121], v[0:1]
	v_mov_b64_e32 v[124:125], v[0:1]
	v_mov_b64_e32 v[132:133], v[0:1]
	v_mov_b64_e32 v[136:137], v[0:1]
	v_mov_b64_e32 v[92:93], v[0:1]
	v_mov_b64_e32 v[96:97], v[0:1]
	v_mov_b64_e32 v[56:57], v[0:1]
	v_mov_b64_e32 v[60:61], v[0:1]
	v_readlane_b32 s43, v254, 34
	s_mov_b32 s51, s0
	s_mov_b32 s50, 0
	s_barrier
	v_readlane_b32 s1, v254, 37
	s_branch .LBB0_22

; #define PG8_STAGE(bufoff, gbase, voff) do { _Pragma("unroll") for (int _i = 0; _i < 2; ++_i) \
;         __builtin_amdgcn_global_load_lds((const unsigned*)((const char*)(gbase) + (voff)[_i]), (LAS unsigned*)(lds + (bufoff) + ldsw + _i * 8192), 16, 0, 0); } while (0)
; #define PG8_WAIT_V(n) asm volatile("s_waitcnt vmcnt(" #n ")" ::: "memory")
; #define PG8_BAR __builtin_amdgcn_s_barrier()
; template <class Epi, class Sched>
; __device__ __forceinline__ void gemm_phase(LAS unsigned char* lds, const Gemm g, const Sched& S, const Epi& E) {
;     ...
;     PG8_STAGE(PG8_SB(0, 0), cB, voffB); PG8_STAGE(PG8_SB(0, 1), cB + hstepB, voffB); PG8_STAGE(PG8_SA(0, 0), cA, voffA); PG8_STAGE(PG8_SA(0, 1), cA + hstepA, voffA);
;     if (wr == 1) PG8_BAR;
;     PG8_WAIT_V(2); PG8_BAR;
;     PG8_STAGE(PG8_SB(1, 0), cB + kstep, voffB); PG8_STAGE(PG8_SA(1, 0), cA + kstep, voffA); PG8_STAGE(PG8_SB(1, 1), cB + hstepB + kstep, voffB);
;     PG8_WAIT_V(6); PG8_BAR;
.LBB0_274:
	v_readlane_b32 s26, v255, 6
	v_mov_b32_e32 v133, v213
	v_readlane_b32 s27, v255, 7
	v_mov_b32_e32 v129, v213
	v_readlane_b32 s24, v255, 2
	v_lshl_add_u64 v[8:9], s[26:27], 0, v[132:133]
	v_lshl_add_u64 v[10:11], s[26:27], 0, v[128:129]
	v_mov_b32_e32 v135, v213
	v_readlane_b32 s25, v255, 3
	s_add_i32 m0, s52, 0x18000
	v_lshl_add_u64 v[8:9], v[8:9], 0, s[12:13]
	v_lshl_add_u64 v[12:13], s[24:25], 0, v[134:135]
	v_mov_b32_e32 v131, v213
	global_load_lds_dwordx4 v[8:9], off
	v_lshl_add_u64 v[8:9], v[10:11], 0, s[12:13]
	s_add_i32 m0, s52, 0x1a000
	s_add_i32 s56, s52, 0x8000
	v_lshl_add_u64 v[14:15], s[24:25], 0, v[130:131]
	global_load_lds_dwordx4 v[8:9], off
	v_lshl_add_u64 v[8:9], v[12:13], 0, s[12:13]
	s_mov_b32 m0, s56
	s_add_i32 s57, s52, 0xa000
	v_readlane_b32 s14, v255, 8
	global_load_lds_dwordx4 v[8:9], off
	v_lshl_add_u64 v[8:9], v[14:15], 0, s[12:13]
	s_mov_b32 m0, s57
	v_readlane_b32 s15, v255, 9
	global_load_lds_dwordx4 v[8:9], off
	s_add_i32 m0, s52, 0x1c000
	v_lshl_add_u64 v[8:9], s[14:15], 0, v[132:133]
	global_load_lds_dwordx4 v[8:9], off
	v_lshl_add_u64 v[8:9], s[14:15], 0, v[128:129]
	s_add_i32 m0, s52, 0x1e000
	v_and_b32_e32 v7, 15, v2
	global_load_lds_dwordx4 v[8:9], off
	s_waitcnt vmcnt(8)
	s_barrier
	v_bfe_u32 v9, v2, 4, 2
	v_lshlrev_b32_e32 v10, 4, v9
	v_lshl_or_b32 v164, s6, 6, v7
	v_lshl_or_b32 v7, v7, 6, v10
	v_lshlrev_b32_e32 v10, 2, v2
	s_and_b32 s14, s5, 3
	s_lshl_b32 s5, s6, 13
	v_and_b32_e32 v10, 32, v10
	v_bitop3_b32 v11, v7, s5, v10 bitop3:0xde
	s_lshl_b32 s5, s14, 12
	v_bfe_u32 v2, v2, 4, 1
	v_bitop3_b32 v165, v7, s5, v10 bitop3:0xde
	v_lshlrev_b32_e32 v7, 2, v2
	v_lshlrev_b32_e32 v8, 3, v9
	s_cmpk_lt_u32 s4, 0x100
	v_sub_co_u32_e32 v138, vcc, 0, v7
	v_cmp_eq_u32_e64 s[38:39], 0, v2
	v_mov_b32_e32 v2, 0x6000000
	v_mov_b32_e32 v7, 0xe000000
	s_cselect_b64 s[4:5], -1, 0
	v_lshl_or_b32 v136, s14, 5, v8
	s_lshl_b32 s6, s14, 4
	v_cndmask_b32_e64 v2, v2, v7, s[38:39]
	v_bfrev_b32_e32 v7, 8
	v_mov_b32_e32 v8, 0xa000000
	v_cndmask_b32_e64 v8, v7, v8, s[38:39]
	v_lshl_or_b32 v7, v9, 2, s6
	v_or_b32_e32 v166, 0xfffff800, v7
	v_lshlrev_b32_e32 v7, 14, v5
	v_and_b32_e32 v7, 0xffff8000, v7
	v_lshl_add_u32 v4, v4, 11, v7
	v_and_b32_e32 v5, 1, v5
	v_lshl_or_b32 v4, v5, 6, v4
	v_lshl_add_u32 v140, v6, 1, v4
	v_lshlrev_b32_e32 v4, 14, v0
	v_and_b32_e32 v4, 0xffff8000, v4
	s_waitcnt vmcnt(6)
	v_subb_co_u32_e64 v139, s[14:15], 0, 0, vcc
	v_lshl_add_u32 v1, v1, 11, v4
	v_and_b32_e32 v0, 1, v0
	v_lshl_or_b32 v0, v0, 6, v1
	v_readlane_b32 s14, v254, 60
	v_mov_b32_e32 v137, v213
	s_mov_b32 s58, 0
	v_mov_b32_e32 v141, v213
	v_lshl_add_u32 v142, v3, 1, v0
	v_mov_b32_e32 v143, v213
	v_add_u32_e32 v167, 0, v11
	v_lshlrev_b32_e32 v144, 1, v8
	v_lshlrev_b32_e32 v146, 1, v2
	v_readlane_b32 s59, v254, 35
	s_mov_b32 s60, s14
	s_barrier
	v_readlane_b32 s15, v254, 61
	s_branch .LBB0_277

; #define PG8_STAGE(bufoff, gbase, voff) do { _Pragma("unroll") for (int _i = 0; _i < 2; ++_i) \
;         __builtin_amdgcn_global_load_lds((const unsigned*)((const char*)(gbase) + (voff)[_i]), (LAS unsigned*)(lds + (bufoff) + ldsw + _i * 8192), 16, 0, 0); } while (0)
; #define PG8_WAIT_V(n) asm volatile("s_waitcnt vmcnt(" #n ")" ::: "memory")
; #define PG8_BAR __builtin_amdgcn_s_barrier()
; template <class Epi, class Sched>
; __device__ __forceinline__ void gemm_phase(LAS unsigned char* lds, const Gemm g, const Sched& S, const Epi& E) {
;     ...
;     PG8_STAGE(PG8_SB(0, 0), cB, voffB); PG8_STAGE(PG8_SB(0, 1), cB + hstepB, voffB); PG8_STAGE(PG8_SA(0, 0), cA, voffA); PG8_STAGE(PG8_SA(0, 1), cA + hstepA, voffA);
;     if (wr == 1) PG8_BAR;
;     PG8_WAIT_V(2); PG8_BAR;
;     PG8_STAGE(PG8_SB(1, 0), cB + kstep, voffB); PG8_STAGE(PG8_SA(1, 0), cA + kstep, voffA); PG8_STAGE(PG8_SB(1, 1), cB + hstepB + kstep, voffB);
;     PG8_WAIT_V(6); PG8_BAR;
.LBB0_500:
	v_lshrrev_b32_e32 v7, 1, v6
	v_and_b32_e32 v17, 24, v7
	v_and_b32_e32 v16, 15, v6
	v_lshlrev_b32_e32 v7, 1, v17
	v_lshlrev_b32_e32 v6, 2, v6
	v_readlane_b32 s26, v254, 44
	s_lshl_b32 s43, s14, 6
	v_lshl_or_b32 v7, v16, 6, v7
	s_lshl_b32 s14, s14, 13
	v_and_b32_e32 v6, 32, v6
	s_lshl_b32 s5, s5, 5
	v_mov_b32_e32 v161, v213
	v_readlane_b32 s27, v254, 45
	v_bitop3_b32 v18, v7, s14, v6 bitop3:0xde
	s_and_b32 s14, s5, 0x60
	v_lshl_add_u64 v[8:9], s[26:27], 0, v[160:161]
	v_mov_b32_e32 v157, v213
	v_readlane_b32 s24, v254, 40
	s_lshl_b32 s5, s14, 7
	v_lshl_add_u64 v[10:11], s[26:27], 0, v[156:157]
	v_mov_b32_e32 v163, v213
	v_readlane_b32 s25, v254, 41
	v_bitop3_b32 v178, v7, s5, v6 bitop3:0xde
	s_add_i32 m0, s6, 0x18000
	v_lshl_add_u64 v[6:7], v[8:9], 0, s[12:13]
	v_lshl_add_u64 v[12:13], s[24:25], 0, v[162:163]
	v_mov_b32_e32 v159, v213
	global_load_lds_dwordx4 v[6:7], off
	v_lshl_add_u64 v[6:7], v[10:11], 0, s[12:13]
	s_add_i32 m0, s6, 0x1a000
	s_add_i32 s44, s6, 0x8000
	v_lshl_add_u64 v[14:15], s[24:25], 0, v[158:159]
	global_load_lds_dwordx4 v[6:7], off
	v_lshl_add_u64 v[6:7], v[12:13], 0, s[12:13]
	s_mov_b32 m0, s44
	s_add_i32 s45, s6, 0xa000
	v_readlane_b32 s16, v254, 46
	global_load_lds_dwordx4 v[6:7], off
	v_lshl_add_u64 v[6:7], v[14:15], 0, s[12:13]
	s_mov_b32 m0, s45
	v_readlane_b32 s17, v254, 47
	global_load_lds_dwordx4 v[6:7], off
	s_add_i32 m0, s6, 0x1c000
	v_lshl_add_u64 v[6:7], s[16:17], 0, v[160:161]
	global_load_lds_dwordx4 v[6:7], off
	v_lshl_add_u64 v[6:7], s[16:17], 0, v[156:157]
	s_add_i32 m0, s6, 0x1e000
	s_cmpk_lt_u32 s4, 0x100
	global_load_lds_dwordx4 v[6:7], off
	s_waitcnt vmcnt(8)
	s_barrier
	v_lshlrev_b32_e32 v7, 14, v4
	v_and_b32_e32 v7, 0xffff8000, v7
	v_lshl_add_u32 v3, v3, 11, v7
	v_and_b32_e32 v4, 1, v4
	v_lshl_or_b32 v3, v4, 6, v3
	v_lshl_add_u32 v164, v5, 1, v3
	v_lshlrev_b32_e32 v3, 14, v0
	v_and_b32_e32 v3, 0xffff8000, v3
	s_waitcnt vmcnt(6)
	v_lshlrev_b32_e32 v6, 10, v16
	v_lshl_add_u32 v1, v1, 11, v3
	v_and_b32_e32 v0, 1, v0
	v_or3_b32 v6, v17, v6, s14
	v_lshl_or_b32 v0, v0, 6, v1
	v_readlane_b32 s14, v254, 36
	s_cselect_b64 s[4:5], -1, 0
	v_mov_b32_e32 v165, v213
	v_lshl_add_u32 v166, v2, 1, v0
	v_mov_b32_e32 v167, v213
	s_mov_b32 s46, 0
	v_add_u32_e32 v179, 0, v18
	v_lshlrev_b32_e32 v212, 1, v6
	v_readlane_b32 s47, v254, 34
	s_mov_b32 s48, s14
	s_barrier
	v_readlane_b32 s15, v254, 37
	s_branch .LBB0_503
